# prologue phase: the read-once f32 x rows of the x->bf16 conversion loaded non-temporal
# speedup vs baseline: 1.0202x; 1.0085x over previous
; __device__ __forceinline__ v4u pack8(const float (&f)[8]) { v4u w; w.x = cvt_pk_bf16(f[0], f[1]); w.y = cvt_pk_bf16(f[2], f[3]); w.z = cvt_pk_bf16(f[4], f[5]); w.w = cvt_pk_bf16(f[6], f[7]); return w; }
; __device__ __forceinline__ void ph_p0(const Params& p, LAS unsigned char* lds, int tid, int lane, int wave) {
;     ...
;     for (int r = gw; r < M; r += NGW) {
;         const float* src;
;         if (r < MP) { const int b = r / TP, t = r % TP; src = t < NMETA ? p.in[I_META] + (size_t)t * D : p.in[I_XP] + ((size_t)b * SEQ + (t - NMETA)) * D; }
;         else src = p.in[I_XS] + (size_t)(r - MP) * D;
;         float ss = 0.f;
; #pragma unroll
;         for (int j = 0; j < 2; ++j) { const int c0 = 512 * j + 8 * lane;
;             const f32x4 a4 = *(const f32x4*)(src + c0), b4 = *(const f32x4*)(src + c0 + 4);
;             const float f[8] = {a4.x, a4.y, a4.z, a4.w, b4.x, b4.y, b4.z, b4.w};
; #pragma unroll
;             for (int e = 0; e < 8; ++e) ss += f[e] * f[e];
;             *(v4u*)(XB + (size_t)r * D + c0) = pack8(f); }
;         ss = wave_sum(ss, lane);
;         if (lane < 16) ((float*)(ws + WS_SS))[(size_t)r * 16 + lane] = lane == 0 ? ss : 0.f;
;     }
.LBB0_1545:
	s_lshl_b64 s[8:9], s[10:11], 12
	s_add_u32 s6, s6, s8
	s_addc_u32 s7, s7, s9
	global_load_dwordx4 v[6:9], v0, s[6:7] nt
	s_waitcnt lgkmcnt(0)
	global_load_dwordx4 v[10:13], v0, s[6:7] offset:16 nt
	s_ashr_i32 s3, s2, 31
	s_lshl_b64 s[8:9], s[2:3], 11
	s_waitcnt vmcnt(0)
	v_lshl_add_u64 v[22:23], v[4:5], 0, s[8:9]
	v_cvt_pk_bf16_f32 v14, v6, v7
	v_cvt_pk_bf16_f32 v15, v8, v9
	v_cvt_pk_bf16_f32 v16, v10, v11
	v_cvt_pk_bf16_f32 v17, v12, v13
	global_store_dwordx4 v[22:23], v[14:17], off
	global_load_dwordx4 v[14:17], v0, s[6:7] offset:2048 nt
	s_nop 0
	global_load_dwordx4 v[18:21], v0, s[6:7] offset:2064 nt
	v_mul_f32_e32 v24, v7, v7
	v_fmac_f32_e32 v24, v6, v6
	v_fmac_f32_e32 v24, v8, v8
	v_fmac_f32_e32 v24, v9, v9
	v_fmac_f32_e32 v24, v10, v10
	v_fmac_f32_e32 v24, v11, v11
	v_fmac_f32_e32 v24, v12, v12
	v_fmac_f32_e32 v24, v13, v13
	s_waitcnt vmcnt(1)
	v_cvt_pk_bf16_f32 v6, v14, v15
	v_fmac_f32_e32 v24, v14, v14
	v_fmac_f32_e32 v24, v15, v15
	v_fmac_f32_e32 v24, v16, v16
	v_fmac_f32_e32 v24, v17, v17
	s_waitcnt vmcnt(0)
	v_fmac_f32_e32 v24, v18, v18
	v_fmac_f32_e32 v24, v19, v19
	v_fmac_f32_e32 v24, v20, v20
	v_fmac_f32_e32 v24, v21, v21
	v_cvt_pk_bf16_f32 v7, v16, v17
	v_cvt_pk_bf16_f32 v8, v18, v19
	v_cvt_pk_bf16_f32 v9, v20, v21
	global_store_dwordx4 v[22:23], v[6:9], off offset:1024
	s_nop 1
	v_add_f32_dpp v6, v24, v24 row_ror:8 row_mask:0xf bank_mask:0xf bound_ctrl:1
	s_nop 1
	v_add_f32_dpp v6, v6, v6 row_ror:4 row_mask:0xf bank_mask:0xf bound_ctrl:1
	s_nop 1
	v_add_f32_dpp v6, v6, v6 row_ror:2 row_mask:0xf bank_mask:0xf bound_ctrl:1
	s_nop 1
	v_add_f32_dpp v6, v6, v6 row_ror:1 row_mask:0xf bank_mask:0xf bound_ctrl:1
	s_nop 0
	v_readlane_b32 s8, v6, 0
	v_readlane_b32 s10, v6, 16
	v_readlane_b32 s9, v6, 32
	v_readlane_b32 s11, v6, 48
	s_and_saveexec_b64 s[6:7], s[0:1]
	s_cbranch_execz .LBB0_1537
	v_mov_b32_e32 v8, s10
	v_mov_b32_e32 v9, s11
	v_pk_add_f32 v[8:9], s[8:9], v[8:9]
	s_lshl_b64 s[12:13], s[2:3], 6
	v_add_f32_e32 v8, v8, v9
	v_lshl_add_u64 v[6:7], v[2:3], 0, s[12:13]
	v_cndmask_b32_e64 v8, 0, v8, s[4:5]
	global_store_dword v[6:7], v8, off
	s_branch .LBB0_1537
